# same optimisations on the layout with WD0 transposes hosted in the GU0 tail and barrier 7 grid-wide (fewer transposes inside ATT0)
# baseline (speedup 1.0000x reference)
.LBB0_809:
	s_waitcnt vmcnt(0)
	s_waitcnt vmcnt(0) lgkmcnt(0)
	s_barrier
	s_mov_b64 s[6:7], exec
	v_readlane_b32 s0, v219, 25
	v_readlane_b32 s1, v219, 26
	s_and_b64 s[0:1], s[6:7], s[0:1]
	s_mov_b64 exec, s[0:1]
	s_cbranch_execz .LBB0_861
	v_readlane_b32 s0, v219, 27
	v_readlane_b32 s1, v219, 28
	v_readlane_b32 s2, v219, 30
	s_waitcnt vmcnt(0) lgkmcnt(0)
	buffer_inv sc1
	s_and_b32 s3, s2, 31
	s_lshl_b32 s3, s3, 7
	s_add_i32 s3, s3, 64
	v_mov_b32_e32 v1, s3
	v_mov_b32_e32 v0, 1
	s_nop 1
	global_atomic_add v1, v0, s[0:1]
	v_mov_b32_e32 v2, 0x1040
	global_atomic_add v2, v0, s[0:1]
	s_mov_b32 s15, 0
.Lgb8_spin:
	global_load_dword v2, v1, s[0:1] sc1
	s_waitcnt vmcnt(0)
	v_readfirstlane_b32 s13, v2
	s_nop 1
	s_cmp_ge_u32 s13, 32
	s_cbranch_scc1 .Lgb8_done
	s_sleep 1
	s_add_i32 s15, s15, 1
	s_cmp_lt_u32 s15, 0x200000
	s_cbranch_scc1 .Lgb8_spin

.LBB0_866:
	s_or_b64 exec, exec, s[6:7]
	s_waitcnt vmcnt(0)
	s_barrier
	s_mov_b64 s[6:7], exec
	v_readlane_b32 s0, v219, 25
	v_readlane_b32 s1, v219, 26
	s_and_b64 s[0:1], s[6:7], s[0:1]
	s_mov_b64 exec, s[0:1]
	s_cbranch_execz .LBB0_918
	v_readlane_b32 s0, v219, 27
	v_readlane_b32 s1, v219, 28
	v_readlane_b32 s2, v219, 30
	s_waitcnt vmcnt(0) lgkmcnt(0)
	buffer_inv sc1
	s_and_b32 s3, s2, 31
	s_lshl_b32 s3, s3, 7
	s_add_i32 s3, s3, 64
	v_mov_b32_e32 v1, s3
	v_mov_b32_e32 v0, 1
	s_nop 1
	global_atomic_add v1, v0, s[0:1]
	s_mov_b32 s15, 0
.Lgb9_spin:
	global_load_dword v2, v1, s[0:1] sc1
	s_waitcnt vmcnt(0)
	v_readfirstlane_b32 s13, v2
	s_nop 1
	s_cmp_ge_u32 s13, 40
	s_cbranch_scc1 .Lgb9_done
	s_sleep 1
	s_add_i32 s15, s15, 1
	s_cmp_lt_u32 s15, 0x200000
	s_cbranch_scc1 .Lgb9_spin
.Lgb9_done:
	v_mov_b32_e32 v1, 0x1040
	s_mov_b32 s15, 0

.LBB0_1236:
	s_waitcnt vmcnt(0)
	s_waitcnt vmcnt(0) lgkmcnt(0)
	s_barrier
	s_mov_b64 s[6:7], exec
	v_readlane_b32 s0, v219, 25
	v_readlane_b32 s1, v219, 26
	s_and_b64 s[0:1], s[6:7], s[0:1]
	s_mov_b64 exec, s[0:1]
	s_cbranch_execz .LBB0_1288
	v_readlane_b32 s0, v219, 27
	v_readlane_b32 s1, v219, 28
	v_readlane_b32 s2, v219, 30
	s_waitcnt vmcnt(0) lgkmcnt(0)
	buffer_inv sc1
	s_and_b32 s3, s2, 31
	s_lshl_b32 s3, s3, 7
	s_add_i32 s3, s3, 64
	v_mov_b32_e32 v1, s3
	v_mov_b32_e32 v0, 1
	s_nop 1
	global_atomic_add v1, v0, s[0:1]
	s_mov_b32 s15, 0
.Lgb12_spin:
	global_load_dword v2, v1, s[0:1] sc1
	s_waitcnt vmcnt(0)
	v_readfirstlane_b32 s13, v2
	s_nop 1
	s_cmp_ge_u32 s13, 48
	s_cbranch_scc1 .Lgb12_done
	s_sleep 1
	s_add_i32 s15, s15, 1
	s_cmp_lt_u32 s15, 0x200000
	s_cbranch_scc1 .Lgb12_spin

.LBB0_1293:
	s_or_b64 exec, exec, s[6:7]
	s_waitcnt vmcnt(0)
	s_barrier
	s_mov_b64 s[6:7], exec
	v_readlane_b32 s0, v219, 25
	v_readlane_b32 s1, v219, 26
	s_and_b64 s[0:1], s[6:7], s[0:1]
	s_mov_b64 exec, s[0:1]
	s_cbranch_execz .LBB0_1345
	v_readlane_b32 s0, v219, 27
	v_readlane_b32 s1, v219, 28
	v_readlane_b32 s2, v219, 30
	s_waitcnt vmcnt(0) lgkmcnt(0)
	buffer_inv sc1
	s_and_b32 s3, s2, 31
	s_lshl_b32 s3, s3, 7
	s_add_i32 s3, s3, 64
	v_mov_b32_e32 v1, s3
	v_mov_b32_e32 v0, 1
	s_nop 1
	global_atomic_add v1, v0, s[0:1]
	s_mov_b32 s15, 0
.Lgb13_spin:
	global_load_dword v2, v1, s[0:1] sc1
	s_waitcnt vmcnt(0)
	v_readfirstlane_b32 s13, v2
	s_nop 1
	s_cmp_ge_u32 s13, 56
	s_cbranch_scc1 .Lgb13_done
	s_sleep 1
	s_add_i32 s15, s15, 1
	s_cmp_lt_u32 s15, 0x200000
	s_cbranch_scc1 .Lgb13_spin
.Lgb13_done:
	v_mov_b32_e32 v1, 0x1140
	s_mov_b32 s15, 0

.LBB0_1409:
	s_waitcnt vmcnt(0)
	s_waitcnt vmcnt(0) lgkmcnt(0)
	s_barrier
	s_mov_b64 s[6:7], exec
	v_readlane_b32 s0, v219, 25
	v_readlane_b32 s1, v219, 26
	s_and_b64 s[0:1], s[6:7], s[0:1]
	s_mov_b64 exec, s[0:1]
	s_cbranch_execz .LBB0_1461
	v_readlane_b32 s0, v219, 27
	v_readlane_b32 s1, v219, 28
	v_readlane_b32 s2, v219, 30
	s_waitcnt vmcnt(0) lgkmcnt(0)
	buffer_inv sc1
	s_and_b32 s3, s2, 31
	s_lshl_b32 s3, s3, 7
	s_add_i32 s3, s3, 64
	v_mov_b32_e32 v1, s3
	v_mov_b32_e32 v0, 1
	s_nop 1
	global_atomic_add v1, v0, s[0:1]
	s_mov_b32 s15, 0
.Lgb14_spin:
	global_load_dword v2, v1, s[0:1] sc1
	s_waitcnt vmcnt(0)
	v_readfirstlane_b32 s13, v2
	s_nop 1
	s_cmp_ge_u32 s13, 64
	s_cbranch_scc1 .Lgb14_done
	s_sleep 1
	s_add_i32 s15, s15, 1
	s_cmp_lt_u32 s15, 0x200000
	s_cbranch_scc1 .Lgb14_spin

.LBB0_1525:
	s_waitcnt vmcnt(0)
	s_waitcnt vmcnt(0) lgkmcnt(0)
	s_barrier
	s_mov_b64 s[4:5], exec
	v_readlane_b32 s0, v219, 25
	v_readlane_b32 s1, v219, 26
	s_and_b64 s[0:1], s[4:5], s[0:1]
	s_mov_b64 exec, s[0:1]
	s_cbranch_execz .LBB0_1577
	v_readlane_b32 s0, v219, 27
	v_readlane_b32 s1, v219, 28
	v_readlane_b32 s2, v219, 30
	s_waitcnt vmcnt(0) lgkmcnt(0)
	buffer_inv sc1
	s_and_b32 s3, s2, 31
	s_lshl_b32 s3, s3, 7
	s_add_i32 s3, s3, 64
	v_mov_b32_e32 v1, s3
	v_mov_b32_e32 v0, 1
	s_nop 1
	global_atomic_add v1, v0, s[0:1]
	s_mov_b32 s15, 0
.Lgb15_spin:
	global_load_dword v2, v1, s[0:1] sc1
	s_waitcnt vmcnt(0)
	v_readfirstlane_b32 s13, v2
	s_nop 1
	s_cmp_ge_u32 s13, 72
	s_cbranch_scc1 .Lgb15_done
	s_sleep 1
	s_add_i32 s15, s15, 1
	s_cmp_lt_u32 s15, 0x200000
	s_cbranch_scc1 .Lgb15_spin
